# v20
# baseline (speedup 1.0000x reference)
; __device__ __forceinline__ int opaque_tid() { int t = threadIdx.x; asm volatile("" : "+v"(t)); return t; }
; __device__ __forceinline__ void gemm_prologue(const u16* __restrict__ A, const u16* __restrict__ Bt, const int K,
;                                               const int brow, const int bcol) {
;   int tid = threadIdx.x;
;   asm volatile("" : "+v"(tid));
;   const int tid16 = tid * 16;
;   int goff0, goff1;
;   { int R, C; stage_rc(tid16, R, C); goff0 = R * K + C; stage_rc(tid16 + 8192, R, C); goff1 = R * K + C; }
;   STAGE(SB(0, 0), Bt, bcol, 0); STAGE(SA(0, 0), A, brow, 0);
;   STAGE(SB(0, 1), Bt, bcol + HALF, 0); STAGE(SA(0, 1), A, brow + HALF, 0);
; }
; __device__ void phase1(const Params& p) {
;   const int tid = opaque_tid(), wid = tid >> 6, lane = tid & 63, wr = wid >> 2, wc = wid & 3, fr = lane & 15, fq = lane >> 4;
;   constexpr int NT = 25 * 256;
;   int t = blockIdx.x;
;   if (t < NT) { P1Tile d = p1_tile(p, t); gemm_prologue(d.A, d.B, 4096, d.brow, d.bcol); }
.LBB0_53:
	v_mov_b32_e32 v1, v248
	v_mov_b32_e32 v144, 1
	v_ashrrev_i32_e32 v2, 31, v1
	v_lshrrev_b32_e32 v2, 26, v2
	v_lshlrev_b32_e32 v8, 4, v1
	v_add_u32_e32 v2, v1, v2
	v_bfe_i32 v1, v1, 27, 1
	v_lshrrev_b32_e32 v1, 22, v1
	v_add_u32_e32 v1, v8, v1
	v_and_b32_e32 v1, 0xfffffc00, v1
	v_sub_u32_e32 v1, v8, v1
	v_lshrrev_b32_e32 v3, 4, v1
	v_bitop3_b32 v1, v3, v1, 32 bitop3:0x6c
	v_ashrrev_i32_e32 v4, 31, v1
	v_ashrrev_i32_e32 v2, 6, v2
	v_lshrrev_b32_e32 v4, 26, v4
	v_lshlrev_b32_e32 v3, 3, v2
	v_add_u32_e32 v4, v1, v4
	v_and_b32_e32 v3, 0xffff0, v3
	v_lshrrev_b32_e32 v5, 6, v4
	v_lshlrev_b32_e32 v2, 5, v2
	v_and_b32_e32 v4, 0xc0, v4
	v_add_u32_e32 v3, v5, v3
	v_and_b32_e32 v2, 32, v2
	v_sub_u32_e32 v1, v1, v4
	v_ashrrev_i16_sdwa v1, v144, sext(v1) dst_sel:DWORD dst_unused:UNUSED_PAD src0_sel:DWORD src1_sel:BYTE_0
	v_lshl_or_b32 v2, v3, 12, v2
	v_add_u32_sdwa v2, v2, sext(v1) dst_sel:DWORD dst_unused:UNUSED_PAD src0_sel:DWORD src1_sel:WORD_0
	v_add_u32_e32 v1, 0x2000, v8
	v_ashrrev_i32_e32 v3, 31, v1
	v_lshrrev_b32_e32 v3, 22, v3
	v_add_u32_e32 v3, v1, v3
	v_ashrrev_i32_e32 v3, 10, v3
	v_mul_i32_i24_e32 v4, 0x400, v3
	v_sub_u32_e32 v4, v1, v4
	v_lshrrev_b32_e32 v5, 4, v4
	v_bitop3_b32 v4, v5, v4, 32 bitop3:0x6c
	v_ashrrev_i32_e32 v6, 31, v4
	v_lshrrev_b32_e32 v6, 26, v6
	v_lshlrev_b32_e32 v5, 3, v3
	v_add_u32_e32 v6, v4, v6
	v_and_b32_e32 v5, 0xffff0, v5
	v_lshrrev_b32_e32 v7, 6, v6
	v_lshlrev_b32_e32 v3, 5, v3
	v_and_b32_e32 v6, 0xc0, v6
	v_add_u32_e32 v5, v7, v5
	v_and_b32_e32 v3, 32, v3
	v_sub_u32_e32 v4, v4, v6
	s_ashr_i32 s35, s34, 31
	s_lshl_b32 s28, s2, 8
	v_ashrrev_i16_sdwa v4, v144, sext(v4) dst_sel:DWORD dst_unused:UNUSED_PAD src0_sel:DWORD src1_sel:BYTE_0
	v_lshl_or_b32 v3, v5, 12, v3
	s_lshl_b64 s[2:3], s[34:35], 13
	v_add_u32_sdwa v4, v3, sext(v4) dst_sel:DWORD dst_unused:UNUSED_PAD src0_sel:DWORD src1_sel:WORD_0
	s_add_u32 s2, s30, s2
	v_ashrrev_i32_e32 v3, 31, v2
	v_add_u32_e32 v5, 0x10000, v8
	s_addc_u32 s3, s31, s3
	v_lshlrev_b64 v[2:3], 1, v[2:3]
	v_readfirstlane_b32 s8, v5
	v_ashrrev_i32_e32 v5, 31, v4
	v_lshl_add_u64 v[6:7], s[2:3], 0, v[2:3]
	s_mov_b32 m0, s8
	v_lshlrev_b64 v[4:5], 1, v[4:5]
	v_add_u32_e32 v9, 0x12000, v8
	global_load_lds_dwordx4 v[6:7], off
	v_lshl_add_u64 v[6:7], s[2:3], 0, v[4:5]
	v_readfirstlane_b32 s2, v9
	s_mov_b32 s29, 0
	s_mov_b32 m0, s2
	s_lshl_b64 s[2:3], s[28:29], 13
	s_add_u32 s2, s0, s2
	s_addc_u32 s3, s1, s3
	v_readfirstlane_b32 s8, v8
	global_load_lds_dwordx4 v[6:7], off
	v_lshl_add_u64 v[6:7], s[2:3], 0, v[2:3]
	s_mov_b32 m0, s8
	s_mov_b32 s6, 0x10000
	global_load_lds_dwordx4 v[6:7], off
	v_lshl_add_u64 v[6:7], s[2:3], 0, v[4:5]
	v_readfirstlane_b32 s2, v1
	s_mov_b32 m0, s2
	s_or_b32 s2, s34, 0x80
	s_ashr_i32 s3, s2, 31
	s_lshl_b64 s[2:3], s[2:3], 13
	s_add_u32 s2, s30, s2
	v_add_u32_e32 v1, 0x14000, v8
	s_addc_u32 s3, s31, s3
	v_readfirstlane_b32 s8, v1
	global_load_lds_dwordx4 v[6:7], off
	v_lshl_add_u64 v[6:7], s[2:3], 0, v[2:3]
	s_mov_b32 m0, s8
	v_add_u32_e32 v1, 0x16000, v8
	global_load_lds_dwordx4 v[6:7], off
	v_lshl_add_u64 v[6:7], s[2:3], 0, v[4:5]
	v_readfirstlane_b32 s2, v1
	s_bitset1_b32 s28, 7
	s_mov_b32 m0, s2
	s_lshl_b64 s[2:3], s[28:29], 13
	s_add_u32 s0, s0, s2
	v_add_u32_e32 v1, 0x4000, v8
	s_addc_u32 s1, s1, s3
	v_readfirstlane_b32 s2, v1
	global_load_lds_dwordx4 v[6:7], off
	v_lshl_add_u64 v[2:3], s[0:1], 0, v[2:3]
	s_mov_b32 m0, s2
	v_add_u32_e32 v1, 0x6000, v8
	global_load_lds_dwordx4 v[2:3], off
	v_lshl_add_u64 v[2:3], s[0:1], 0, v[4:5]
	v_readfirstlane_b32 s0, v1
	s_mov_b32 m0, s0
	v_and_b32_e32 v1, 15, v0
	global_load_lds_dwordx4 v[2:3], off
	v_bfe_u32 v3, v0, 6, 2
	v_ashrrev_i32_e32 v2, 2, v0
	s_movk_i32 s0, 0xffc0
	v_and_or_b32 v145, v2, s0, v1
	v_lshrrev_b32_e32 v1, 2, v0
	v_lshlrev_b32_e32 v0, 4, v0
	v_cmp_eq_u32_e64 s[0:1], 0, v3
	v_and_b32_e32 v2, 12, v1
	v_ashrrev_i32_e32 v1, 31, v0
	v_writelane_b32 v255, s0, 10
	s_mov_b32 s7, 0x14000
	v_lshl_or_b32 v146, v3, 5, v2
	v_writelane_b32 v255, s1, 11
	v_mov_b32_e32 v133, 0
	v_lshl_add_u64 v[134:135], s[36:37], 0, v[0:1]
	s_mov_b64 s[30:31], 0x80
	s_mov_b32 s3, 0x1c000
	s_mov_b64 s[34:35], 0x100080
	s_mov_b64 s[56:57], 0x100
	s_mov_b64 s[58:59], 0x100100
	s_mov_b64 s[84:85], 0x180
	s_mov_b64 s[86:87], 0x100180
	v_lshlrev_b32_e32 v132, 2, v2
	s_mov_b32 s2, s10
	s_waitcnt vmcnt(0)
	s_branch .LBB0_56

; #define WAIT_V(n) asm volatile("s_waitcnt vmcnt(" #n ")" ::: "memory")
; #define BAR __builtin_amdgcn_s_barrier()
; __device__ __forceinline__ void gemm_main(const u16* __restrict__ A, const u16* __restrict__ Bt, const int K, const int Klen,
;                                           const int brow, const int bcol, f32x4 (&acc)[2][2][4][2]) {
;     ...
;   const int wid = tid >> 6, lane = tid & 63, wr = wid >> 2, wc = wid & 3, fr = lane & 15, fq = lane >> 4;
;   const int tid16 = tid * 16;
;   int goff0, goff1;
;   { int R, C; stage_rc(tid16, R, C); goff0 = R * K + C; stage_rc(tid16 + 8192, R, C); goff1 = R * K + C; }
;   bf16x8 At[4][2], B0[2][2], B1[2][2];
;   const int nt = Klen / BK;
;   if (wr == 1) BAR;
;   WAIT_V(4); BAR;
.LBB0_63:
	s_or_b64 exec, exec, s[0:1]
	v_ashrrev_i32_e32 v2, 31, v147
	v_lshrrev_b32_e32 v2, 26, v2
	v_add_u32_e32 v2, v147, v2
	v_ashrrev_i32_e32 v9, 6, v2
	v_bfe_i32 v2, v147, 27, 1
	v_lshlrev_b32_e32 v152, 4, v147
	v_lshrrev_b32_e32 v2, 22, v2
	v_add_u32_e32 v2, v152, v2
	v_and_b32_e32 v2, 0xfffffc00, v2
	v_sub_u32_e32 v2, v152, v2
	v_lshrrev_b32_e32 v3, 4, v2
	v_bitop3_b32 v2, v3, v2, 32 bitop3:0x6c
	v_ashrrev_i32_e32 v4, 31, v2
	v_lshrrev_b32_e32 v4, 26, v4
	v_lshlrev_b32_e32 v3, 3, v9
	v_add_u32_e32 v4, v2, v4
	v_and_b32_e32 v3, 0xffff0, v3
	v_ashrrev_i32_e32 v10, 6, v4
	v_lshlrev_b32_e32 v5, 5, v9
	v_and_b32_e32 v4, 0xc0, v4
	v_add_u32_e32 v3, v10, v3
	v_and_b32_e32 v11, 32, v5
	v_sub_u32_e32 v2, v2, v4
	v_ashrrev_i16_sdwa v12, v144, sext(v2) dst_sel:DWORD dst_unused:UNUSED_PAD src0_sel:DWORD src1_sel:BYTE_0
	v_lshl_or_b32 v2, v3, 12, v11
	v_add_u32_e32 v154, 0x2000, v152
	v_add_u32_sdwa v128, v2, sext(v12) dst_sel:DWORD dst_unused:UNUSED_PAD src0_sel:DWORD src1_sel:WORD_0
	v_ashrrev_i32_e32 v2, 31, v154
	v_lshrrev_b32_e32 v2, 22, v2
	v_add_u32_e32 v2, v154, v2
	v_ashrrev_i32_e32 v13, 10, v2
	v_mul_i32_i24_e32 v2, 0x400, v13
	v_sub_u32_e32 v2, v154, v2
	v_lshrrev_b32_e32 v3, 4, v2
	v_bitop3_b32 v2, v3, v2, 32 bitop3:0x6c
	v_ashrrev_i32_e32 v4, 31, v2
	v_lshrrev_b32_e32 v4, 26, v4
	v_lshlrev_b32_e32 v3, 3, v13
	v_add_u32_e32 v4, v2, v4
	v_and_b32_e32 v3, 0xffff0, v3
	v_ashrrev_i32_e32 v14, 6, v4
	v_lshlrev_b32_e32 v5, 5, v13
	v_and_b32_e32 v4, 0xc0, v4
	s_ashr_i32 s93, s92, 31
	s_lshl_b32 s28, s11, 8
	v_add_u32_e32 v3, v14, v3
	v_and_b32_e32 v15, 32, v5
	v_sub_u32_e32 v2, v2, v4
	s_lshl_b64 s[0:1], s[92:93], 13
	v_ashrrev_i16_sdwa v16, v144, sext(v2) dst_sel:DWORD dst_unused:UNUSED_PAD src0_sel:DWORD src1_sel:BYTE_0
	v_lshl_or_b32 v2, v3, 12, v15
	s_add_u32 s0, s94, s0
	v_ashrrev_i32_e32 v129, 31, v128
	v_add_u32_sdwa v130, v2, sext(v16) dst_sel:DWORD dst_unused:UNUSED_PAD src0_sel:DWORD src1_sel:WORD_0
	s_addc_u32 s1, s95, s1
	v_lshlrev_b64 v[2:3], 1, v[128:129]
	v_add_u32_e32 v156, 0x18000, v152
	v_lshl_add_u64 v[4:5], s[0:1], 0, v[2:3]
	v_readfirstlane_b32 s8, v156
	v_lshl_add_u64 v[4:5], v[4:5], 0, s[30:31]
	s_mov_b32 m0, s8
	v_ashrrev_i32_e32 v131, 31, v130
	s_waitcnt vmcnt(20)
	s_barrier
; #define WAIT_V(n) asm volatile("s_waitcnt vmcnt(" #n ")" ::: "memory")
; #define BAR __builtin_amdgcn_s_barrier()
; __device__ __forceinline__ void gemm_main(const u16* __restrict__ A, const u16* __restrict__ Bt, const int K, const int Klen,
;                                           const int brow, const int bcol, f32x4 (&acc)[2][2][4][2]) {
;     ...
;   STAGE(SB(1, 0), Bt, bcol, 1); STAGE(SA(1, 0), A, brow, 1); STAGE(SB(1, 1), Bt, bcol + HALF, 1);
;   WAIT_V(6); BAR;
; __device__ void phase1(const Params& p) {
;     ...
;     f32x4 acc[2][2][4][2] = {};
	global_load_lds_dwordx4 v[4:5], off
	v_lshlrev_b64 v[4:5], 1, v[130:131]
	v_add_u32_e32 v157, 0x1a000, v152
	s_lshl_b64 vcc, s[28:29], 13
	v_lshl_add_u64 v[6:7], s[0:1], 0, v[4:5]
	v_readfirstlane_b32 s8, v157
	s_add_u32 vcc_lo, s90, vcc_lo
	v_lshl_add_u64 v[6:7], v[6:7], 0, s[30:31]
	s_mov_b32 m0, s8
	s_addc_u32 vcc_hi, s91, vcc_hi
	v_add_u32_e32 v158, 0x8000, v152
	global_load_lds_dwordx4 v[6:7], off
	v_lshl_add_u64 v[6:7], vcc, 0, v[2:3]
	v_readfirstlane_b32 s8, v158
	v_add_u32_e32 v159, 0xa000, v152
	v_lshl_add_u64 v[6:7], v[6:7], 0, s[30:31]
	s_mov_b32 m0, s8
	v_readfirstlane_b32 s8, v159
	global_load_lds_dwordx4 v[6:7], off
	s_mov_b32 m0, s8
	s_or_b32 s8, s92, 0x80
	s_ashr_i32 s9, s8, 31
	s_lshl_b64 s[8:9], s[8:9], 13
	s_add_u32 s8, s94, s8
	v_lshl_add_u64 v[6:7], vcc, 0, v[4:5]
	s_addc_u32 s9, s95, s9
	v_add_u32_e32 v161, 0x1c000, v152
	v_lshl_add_u64 v[6:7], v[6:7], 0, s[30:31]
	v_lshl_add_u64 v[2:3], s[8:9], 0, v[2:3]
	v_readfirstlane_b32 s93, v161
	global_load_lds_dwordx4 v[6:7], off
	v_lshl_add_u64 v[2:3], v[2:3], 0, s[30:31]
	s_mov_b32 m0, s93
	v_add_u32_e32 v163, 0x1e000, v152
	global_load_lds_dwordx4 v[2:3], off
	v_lshl_add_u64 v[2:3], s[8:9], 0, v[4:5]
	v_readfirstlane_b32 s8, v163
	v_lshl_add_u64 v[2:3], v[2:3], 0, s[30:31]
	s_mov_b32 m0, s8
	v_and_b32_e32 v1, 15, v147
	global_load_lds_dwordx4 v[2:3], off
	v_lshlrev_b32_e32 v3, 2, v147
	v_and_b32_e32 v8, 48, v147
	v_lshlrev_b32_e32 v1, 6, v1
	v_and_b32_e32 v3, 32, v3
	v_or_b32_e32 v2, v1, v8
	v_bitop3_b32 v4, v1, v3, v8 bitop3:0x36
	v_lshlrev_b32_e32 v1, 6, v147
	v_lshlrev_b32_e32 v19, 13, v0
	v_and_b32_e32 v0, 0x3c0, v1
	s_mov_b32 s8, 0x18000
	v_bitop3_b32 v8, v0, v3, v8 bitop3:0x36
	v_lshlrev_b32_e32 v0, 15, v9
	v_bitop3_b32 v5, v2, s6, v3 bitop3:0xde
	v_bitop3_b32 v6, v2, s7, v3 bitop3:0xde
	v_bitop3_b32 v7, v2, s8, v3 bitop3:0xde
	v_bitop3_b32 v17, v2, s3, v3 bitop3:0xde
	v_and_b32_e32 v0, 0xffff0000, v0
	v_lshlrev_b32_e32 v2, 15, v13
	v_lshl_add_u32 v0, v10, 12, v0
	v_and_b32_e32 v2, 0xffff0000, v2
	v_or_b32_e32 v0, v0, v11
	v_lshl_add_u32 v2, v14, 12, v2
	v_add_u32_sdwa v0, v0, sext(v12) dst_sel:DWORD dst_unused:UNUSED_PAD src0_sel:DWORD src1_sel:WORD_0
	v_or_b32_e32 v2, v2, v15
	v_and_b32_e32 v18, 0x3000, v1
	v_ashrrev_i32_e32 v1, 31, v0
	v_add_u32_sdwa v2, v2, sext(v16) dst_sel:DWORD dst_unused:UNUSED_PAD src0_sel:DWORD src1_sel:WORD_0
	s_waitcnt vmcnt(22)
	v_lshlrev_b64 v[0:1], 1, v[0:1]
	v_ashrrev_i32_e32 v3, 31, v2
	v_or_b32_e32 v20, 0x800, v19
	v_or_b32_e32 v21, 0x1000, v19
	v_or_b32_e32 v22, 0x1800, v19
	v_lshl_add_u64 v[136:137], s[0:1], 0, v[0:1]
	v_lshlrev_b64 v[2:3], 1, v[2:3]
	v_lshl_add_u64 v[140:141], vcc, 0, v[0:1]
	v_mov_b32_e32 v0, 0
	s_add_i32 s93, s96, -2
	v_lshl_add_u64 v[138:139], s[0:1], 0, v[2:3]
	v_lshl_add_u64 v[142:143], vcc, 0, v[2:3]
	s_mov_b32 s0, 0
	s_mov_b64 s[94:95], 0
	v_add_u32_e32 v166, v5, v18
	v_add_u32_e32 v151, v4, v19
	v_add_u32_e32 v150, v8, v20
	v_add_u32_e32 v149, v8, v21
	v_add_u32_e32 v148, v8, v22
	v_add_u32_e32 v165, 0xc000, v152
	v_add_u32_e32 v164, 0xe000, v152
	v_add_u32_e32 v162, v6, v18
	v_add_u32_e32 v167, 0x10000, v152
	v_add_u32_e32 v168, 0x12000, v152
	v_add_u32_e32 v169, 0x14000, v152
	v_add_u32_e32 v170, 0x16000, v152
	v_add_u32_e32 v155, v7, v18
	v_add_u32_e32 v171, 0x4000, v152
	v_add_u32_e32 v172, 0x6000, v152
	v_add_u32_e32 v153, v17, v18
	v_mov_b32_e32 v1, v0
	v_mov_b32_e32 v2, v0
	v_mov_b32_e32 v3, v0
	v_mov_b32_e32 v4, v0
	v_mov_b32_e32 v5, v0
	v_mov_b32_e32 v6, v0
	v_mov_b32_e32 v7, v0
	v_mov_b32_e32 v8, v0
	v_mov_b32_e32 v9, v0
	v_mov_b32_e32 v10, v0
	v_mov_b32_e32 v11, v0
	v_mov_b32_e32 v12, v0
	v_mov_b32_e32 v13, v0
	v_mov_b32_e32 v14, v0
	v_mov_b32_e32 v15, v0
	v_mov_b32_e32 v16, v0
	v_mov_b32_e32 v17, v0
	v_mov_b32_e32 v18, v0
	v_mov_b32_e32 v19, v0
	v_mov_b32_e32 v20, v0
	v_mov_b32_e32 v21, v0
	v_mov_b32_e32 v22, v0
	v_mov_b32_e32 v23, v0
	v_mov_b32_e32 v24, v0
	v_mov_b32_e32 v25, v0
	v_mov_b32_e32 v26, v0
	v_mov_b32_e32 v27, v0
	v_mov_b32_e32 v28, v0
	v_mov_b32_e32 v29, v0
	v_mov_b32_e32 v30, v0
	v_mov_b32_e32 v31, v0
	v_mov_b32_e32 v32, v0
	v_mov_b32_e32 v33, v0
	v_mov_b32_e32 v34, v0
	v_mov_b32_e32 v35, v0
	v_mov_b32_e32 v36, v0
	v_mov_b32_e32 v37, v0
	v_mov_b32_e32 v38, v0
	v_mov_b32_e32 v39, v0
	v_mov_b32_e32 v40, v0
	v_mov_b32_e32 v41, v0
	v_mov_b32_e32 v42, v0
	v_mov_b32_e32 v43, v0
	v_mov_b32_e32 v44, v0
	v_mov_b32_e32 v45, v0
	v_mov_b32_e32 v46, v0
	v_mov_b32_e32 v47, v0
	v_mov_b32_e32 v48, v0
	v_mov_b32_e32 v49, v0
	v_mov_b32_e32 v50, v0
	v_mov_b32_e32 v51, v0
	v_mov_b32_e32 v52, v0
	v_mov_b32_e32 v53, v0
	v_mov_b32_e32 v54, v0
	v_mov_b32_e32 v55, v0
	v_mov_b32_e32 v56, v0
	v_mov_b32_e32 v57, v0
	v_mov_b32_e32 v58, v0
	v_mov_b32_e32 v59, v0
	v_mov_b32_e32 v60, v0
	v_mov_b32_e32 v61, v0
	v_mov_b32_e32 v62, v0
	v_mov_b32_e32 v63, v0
	v_mov_b32_e32 v64, v0
	v_mov_b32_e32 v65, v0
	v_mov_b32_e32 v66, v0
	v_mov_b32_e32 v67, v0
	v_mov_b32_e32 v68, v0
	v_mov_b32_e32 v69, v0
	v_mov_b32_e32 v70, v0
	v_mov_b32_e32 v71, v0
	v_mov_b32_e32 v72, v0
	v_mov_b32_e32 v73, v0
	v_mov_b32_e32 v74, v0
	v_mov_b32_e32 v75, v0
	v_mov_b32_e32 v76, v0
	v_mov_b32_e32 v77, v0
	v_mov_b32_e32 v78, v0
	v_mov_b32_e32 v79, v0
	v_mov_b32_e32 v80, v0
	v_mov_b32_e32 v81, v0
	v_mov_b32_e32 v82, v0
	v_mov_b32_e32 v83, v0
	v_mov_b32_e32 v84, v0
	v_mov_b32_e32 v85, v0
	v_mov_b32_e32 v86, v0
	v_mov_b32_e32 v87, v0
	v_mov_b32_e32 v88, v0
	v_mov_b32_e32 v89, v0
	v_mov_b32_e32 v90, v0
	v_mov_b32_e32 v91, v0
	v_mov_b32_e32 v92, v0
	v_mov_b32_e32 v93, v0
	v_mov_b32_e32 v94, v0
	v_mov_b32_e32 v95, v0
	v_mov_b32_e32 v96, v0
	v_mov_b32_e32 v97, v0
	v_mov_b32_e32 v98, v0
	v_mov_b32_e32 v99, v0
	v_mov_b32_e32 v100, v0
	v_mov_b32_e32 v101, v0
	v_mov_b32_e32 v102, v0
	v_mov_b32_e32 v103, v0
	v_mov_b32_e32 v104, v0
	v_mov_b32_e32 v105, v0
	v_mov_b32_e32 v106, v0
	v_mov_b32_e32 v107, v0
	v_mov_b32_e32 v108, v0
	v_mov_b32_e32 v109, v0
	v_mov_b32_e32 v110, v0
	v_mov_b32_e32 v111, v0
	v_mov_b32_e32 v112, v0
	v_mov_b32_e32 v113, v0
	v_mov_b32_e32 v114, v0
	v_mov_b32_e32 v115, v0
	v_mov_b32_e32 v116, v0
	v_mov_b32_e32 v117, v0
	v_mov_b32_e32 v118, v0
	v_mov_b32_e32 v119, v0
	v_mov_b32_e32 v120, v0
	v_mov_b32_e32 v121, v0
	v_mov_b32_e32 v122, v0
	v_mov_b32_e32 v123, v0
	v_mov_b32_e32 v124, v0
	v_mov_b32_e32 v125, v0
	v_mov_b32_e32 v126, v0
	v_mov_b32_e32 v127, v0
	s_barrier
